# in-proj tile order changed to 4 M-tiles x N-major windows (W tiles stay in L2), ctx out-proj epilogue software-pipelined
# speedup vs baseline: 1.0878x; 1.0152x over previous
; #define RAW_BARRIER() do { asm volatile("s_waitcnt lgkmcnt(0)" ::: "memory"); __builtin_amdgcn_s_barrier(); } while (0)
; template <int WM, class Epi>
; DI void gemm_mfma(const bf16_t* __restrict__ A, const bf16_t* __restrict__ Bt, int Arows, int Brows, int MT, int NT, unsigned char* smem, int bid, int nb, int wave, Epi epi) {
;     ...
;   for (int li = l0; li < per; li += lstep) {
;     const int wi = xq * per + li;
;     const int patch = wi / (PM * PN), within = wi % (PM * PN);
;     const int mt = epi.mt_of((patch / NPN) * PM + within / PN), nt = (patch % NPN) * PN + within % PN;
;     f32x16 acc[WM][2];
; #pragma unroll
;     for (int a = 0; a < WM; ++a)
; #pragma unroll
;       for (int b = 0; b < 2; ++b)
; #pragma unroll
;         for (int i = 0; i < 16; ++i) acc[a][b][i] = 0.f;
;     constexpr int NAW = NA / 4;
;     const int wvu = __builtin_amdgcn_readfirstlane(wv);
;     const unsigned voff = (unsigned)((lrow * 32 + ((lpc ^ ((lrow >> 2) & 3)) << 3)) * 2);
;     const char* abase = (const char*)(A + (size_t)(mt * BMROWS + wvu * NAW * 16) * 32);
;     const char* bbase = (const char*)(Bt + (size_t)(nt * 128 + wvu * 2 * 16) * 32);
;     const size_t astep = (size_t)Arows * 64, bstep = (size_t)Brows * 64;
;     auto issue = [&](int kt, int buf) {
; #pragma unroll
;       for (int i = 0; i < NAW; ++i)
;         __builtin_amdgcn_global_load_lds((const unsigned*)(abase + kt * astep + i * 1024 + voff),
;                                          (__attribute__((address_space(3))) unsigned*)(smem + buf * STAGE + (wvu * NAW + i) * 1024), 16, 0, 0);
; #pragma unroll
;       for (int i = 0; i < 2; ++i)
;         __builtin_amdgcn_global_load_lds((const unsigned*)(bbase + kt * bstep + i * 1024 + voff),
;                                          (__attribute__((address_space(3))) unsigned*)(smem + buf * STAGE + A_BYTES + (wvu * 2 + i) * 1024), 16, 0, 0);
;     };
;     RAW_BARRIER();
;     constexpr int NST = (WM == 2) ? 4 : 3;
;     constexpr int NKT = K / 32;
; #pragma unroll
;     for (int s = 0; s < NST - 1; ++s) issue(s, s);
;     bf16x8 fa0[WM], fb0[2], fa1[WM], fb1[2];
; #pragma unroll
;     for (int mi = 0; mi < WM; ++mi) { fa0[mi] = bf16x8{0, 0, 0, 0, 0, 0, 0, 0}; fa1[mi] = fa0[mi]; }
;     fb0[0] = bf16x8{0, 0, 0, 0, 0, 0, 0, 0}; fb0[1] = fb0[0]; fb1[0] = fb0[0]; fb1[1] = fb0[0];
.LBB0_163:
	v_readlane_b32 s0, v254, 0
	s_add_i32 s0, s35, s0
	s_lshr_b32 s1, s0, 2
	s_mul_i32 s1, s1, 0x751
	s_lshr_b32 s1, s1, 16
	s_mul_i32 s4, s1, 0x8c
	s_sub_i32 s0, s0, s4
	s_and_b32 s4, s0, 3
	s_lshr_b32 s0, s0, 2
	s_mov_b32 s29, s0
	s_mov_b32 s8, s0
	v_readfirstlane_b32 s20, v156
	s_lshl_b32 s0, s1, 10
	s_lshl_b32 s28, s4, 8
	s_add_i32 s28, s28, s0
	s_lshl_b32 s0, s20, 6
	s_add_i32 s0, s28, s0
	s_ashr_i32 s1, s0, 31
	s_lshl_b64 s[4:5], s[0:1], 6
	s_add_u32 s6, s2, s4
	s_addc_u32 s7, s30, s5
	s_lshl_b32 s24, s8, 7
	s_lshl_b32 s0, s20, 5
	s_add_i32 s0, s24, s0
	s_ashr_i32 s1, s0, 31
	s_lshl_b64 s[0:1], s[0:1], 6
	s_add_u32 s0, s31, s0
	s_addc_u32 s1, s34, s1
	s_lshl_b32 s9, s20, 12
	v_lshl_add_u64 v[0:1], s[6:7], 0, v[152:153]
	s_mov_b32 m0, s9
	s_mov_b64 s[6:7], 0x400
	s_waitcnt lgkmcnt(0)
	s_barrier
	global_load_lds_dwordx4 v[0:1], off
	v_lshl_add_u64 v[2:3], v[0:1], 0, s[6:7]
	s_or_b32 m0, s9, 0x400
	s_mov_b64 s[26:27], 0x800
	global_load_lds_dwordx4 v[2:3], off
	v_lshl_add_u64 v[2:3], v[0:1], 0, s[26:27]
	s_or_b32 m0, s9, 0x800
	s_mov_b64 s[26:27], 0xc00
	s_lshl_b32 s20, s20, 11
	global_load_lds_dwordx4 v[2:3], off
	v_lshl_add_u64 v[2:3], v[0:1], 0, s[26:27]
	s_or_b32 m0, s9, 0xc00
	v_mov_b32_e32 v128, 0
	global_load_lds_dwordx4 v[2:3], off
	v_lshl_add_u64 v[2:3], s[0:1], 0, v[152:153]
	s_add_i32 m0, s20, 0x4000
	v_lshl_add_u64 v[4:5], v[2:3], 0, s[6:7]
	global_load_lds_dwordx4 v[2:3], off
	s_add_i32 m0, s20, 0x4400
	s_mov_b64 s[6:7], 0x120000
	global_load_lds_dwordx4 v[4:5], off
	v_lshl_add_u64 v[4:5], v[0:1], 0, s[6:7]
	s_add_i32 m0, s9, 0x6000
	s_mov_b64 s[6:7], 0x120400
	global_load_lds_dwordx4 v[4:5], off
	v_lshl_add_u64 v[4:5], v[0:1], 0, s[6:7]
	s_add_i32 m0, s9, 0x6400
	s_mov_b64 s[6:7], 0x120800
	global_load_lds_dwordx4 v[4:5], off
	v_lshl_add_u64 v[4:5], v[0:1], 0, s[6:7]
	s_add_i32 m0, s9, 0x6800
	s_mov_b64 s[6:7], 0x120c00
	global_load_lds_dwordx4 v[4:5], off
	v_lshl_add_u64 v[0:1], v[0:1], 0, s[6:7]
	s_add_i32 m0, s9, 0x6c00
	s_mov_b64 s[6:7], 0x46000
	global_load_lds_dwordx4 v[0:1], off
	v_lshl_add_u64 v[0:1], v[2:3], 0, s[6:7]
	s_add_i32 m0, s20, 0xa000
	s_mov_b64 s[6:7], 0x46400
	global_load_lds_dwordx4 v[0:1], off
	v_lshl_add_u64 v[0:1], v[2:3], 0, s[6:7]
	s_add_i32 m0, s20, 0xa400
	s_add_u32 s4, s68, s4
	global_load_lds_dwordx4 v[0:1], off
	v_mov_b32_e32 v0, 0
	s_addc_u32 s5, s69, s5
	s_mov_b32 s21, 2
	v_mov_b32_e32 v1, v0
	v_mov_b32_e32 v2, v0
	v_mov_b32_e32 v3, v0
	v_mov_b32_e32 v4, v0
	v_mov_b32_e32 v5, v0
	v_mov_b32_e32 v6, v0
	v_mov_b32_e32 v7, v0
	v_mov_b32_e32 v8, v0
	v_mov_b32_e32 v9, v0
	v_mov_b32_e32 v10, v0
	v_mov_b32_e32 v11, v0
	v_mov_b32_e32 v12, v0
	v_mov_b32_e32 v13, v0
	v_mov_b32_e32 v14, v0
	v_mov_b32_e32 v15, v0
	v_mov_b32_e32 v16, v0
	v_mov_b32_e32 v17, v0
	v_mov_b32_e32 v18, v0
	v_mov_b32_e32 v19, v0
	v_mov_b32_e32 v20, v0
	v_mov_b32_e32 v21, v0
	v_mov_b32_e32 v22, v0
	v_mov_b32_e32 v23, v0
	v_mov_b32_e32 v24, v0
	v_mov_b32_e32 v25, v0
	v_mov_b32_e32 v26, v0
	v_mov_b32_e32 v27, v0
	v_mov_b32_e32 v28, v0
	v_mov_b32_e32 v29, v0
	v_mov_b32_e32 v30, v0
	v_mov_b32_e32 v31, v0
	v_mov_b32_e32 v32, v0
	v_mov_b32_e32 v33, v0
	v_mov_b32_e32 v34, v0
	v_mov_b32_e32 v35, v0
	v_mov_b32_e32 v36, v0
	v_mov_b32_e32 v37, v0
	v_mov_b32_e32 v38, v0
	v_mov_b32_e32 v39, v0
	v_mov_b32_e32 v40, v0
	v_mov_b32_e32 v41, v0
	v_mov_b32_e32 v42, v0
	v_mov_b32_e32 v43, v0
	v_mov_b32_e32 v44, v0
	v_mov_b32_e32 v45, v0
	v_mov_b32_e32 v46, v0
	v_mov_b32_e32 v47, v0
	v_mov_b32_e32 v48, v0
	v_mov_b32_e32 v49, v0
	v_mov_b32_e32 v50, v0
	v_mov_b32_e32 v51, v0
	v_mov_b32_e32 v52, v0
	v_mov_b32_e32 v53, v0
	v_mov_b32_e32 v54, v0
	v_mov_b32_e32 v55, v0
	v_mov_b32_e32 v56, v0
	v_mov_b32_e32 v57, v0
	v_mov_b32_e32 v58, v0
	v_mov_b32_e32 v59, v0
	v_mov_b32_e32 v60, v0
	v_mov_b32_e32 v61, v0
	v_mov_b32_e32 v62, v0
	v_mov_b32_e32 v63, v0
	v_mov_b32_e32 v64, v0
	v_mov_b32_e32 v65, v0
	v_mov_b32_e32 v66, v0
	v_mov_b32_e32 v67, v0
	v_mov_b32_e32 v68, v0
	v_mov_b32_e32 v69, v0
	v_mov_b32_e32 v70, v0
	v_mov_b32_e32 v71, v0
	v_mov_b32_e32 v72, v0
	v_mov_b32_e32 v73, v0
	v_mov_b32_e32 v74, v0
	v_mov_b32_e32 v75, v0
	v_mov_b32_e32 v76, v0
	v_mov_b32_e32 v77, v0
	v_mov_b32_e32 v78, v0
	v_mov_b32_e32 v79, v0
	v_mov_b32_e32 v80, v0
	v_mov_b32_e32 v81, v0
	v_mov_b32_e32 v82, v0
	v_mov_b32_e32 v83, v0
	v_mov_b32_e32 v84, v0
	v_mov_b32_e32 v85, v0
	v_mov_b32_e32 v86, v0
	v_mov_b32_e32 v87, v0
	v_mov_b32_e32 v88, v0
	v_mov_b32_e32 v89, v0
	v_mov_b32_e32 v90, v0
	v_mov_b32_e32 v91, v0
	v_mov_b32_e32 v92, v0
	v_mov_b32_e32 v93, v0
	v_mov_b32_e32 v94, v0
	v_mov_b32_e32 v95, v0
	v_mov_b32_e32 v96, v0
	v_mov_b32_e32 v97, v0
	v_mov_b32_e32 v98, v0
	v_mov_b32_e32 v99, v0
	v_mov_b32_e32 v100, v0
	v_mov_b32_e32 v101, v0
	v_mov_b32_e32 v102, v0
	v_mov_b32_e32 v103, v0
	v_mov_b32_e32 v104, v0
	v_mov_b32_e32 v105, v0
	v_mov_b32_e32 v106, v0
	v_mov_b32_e32 v107, v0
	v_mov_b32_e32 v108, v0
	v_mov_b32_e32 v109, v0
	v_mov_b32_e32 v110, v0
	v_mov_b32_e32 v111, v0
	v_mov_b32_e32 v112, v0
	v_mov_b32_e32 v113, v0
	v_mov_b32_e32 v114, v0
	v_mov_b32_e32 v115, v0
	v_mov_b32_e32 v116, v0
	v_mov_b32_e32 v117, v0
	v_mov_b32_e32 v118, v0
	v_mov_b32_e32 v119, v0
	v_mov_b32_e32 v120, v0
	v_mov_b32_e32 v121, v0
	v_mov_b32_e32 v122, v0
	v_mov_b32_e32 v123, v0
	v_mov_b32_e32 v124, v0
	v_mov_b32_e32 v125, v0
	v_mov_b32_e32 v126, v0
	v_mov_b32_e32 v127, v0
	v_mov_b32_e32 v129, v128
	v_mov_b32_e32 v130, v128
	v_mov_b32_e32 v131, v128
	v_mov_b32_e32 v132, v128
	v_mov_b32_e32 v133, v128
	v_mov_b32_e32 v134, v128
	v_mov_b32_e32 v135, v128
	v_mov_b32_e32 v140, v128
	v_mov_b32_e32 v141, v128
	v_mov_b32_e32 v142, v128
	v_mov_b32_e32 v143, v128
	v_mov_b32_e32 v148, v128
	v_mov_b32_e32 v149, v128
	v_mov_b32_e32 v150, v128
	v_mov_b32_e32 v151, v128
	v_mov_b32_e32 v136, v128
	v_mov_b32_e32 v137, v128
	v_mov_b32_e32 v138, v128
	v_mov_b32_e32 v139, v128
	v_mov_b32_e32 v144, v128
	v_mov_b32_e32 v145, v128
	v_mov_b32_e32 v146, v128
	v_mov_b32_e32 v147, v128
	s_branch .LBB0_165

;   DI void operator()(int mt, int nt, int wm, int wn, int r, int h, f32x16 (&acc)[WM][2]) const {
;     ...
; #pragma unroll 4
;       for (int j = 0; j < 16; ++j) {
;         const int id = tid + 256 * j;
;         const int lr = id >> 5, cc = id & 31;
;         const int row = mt * (WM * 64) + (lr >> 6) * (WM * 32) + ps * 64 + (lr & 63);
;         const int b = row / NTOK, t = row % NTOK;
;         const bool isctx = t < NCTX;
;         if (isctx && l == 1) continue;
;         const int col = nt * 128 + cc * 4;
;         const float4 a = *(const float4*)(T + lr * LD + cc * 4);
;         const float4 g = *(const float4*)(MOD + ((size_t)l * 9 + (isctx ? 8 : b)) * 3072 + 2048 + col);
;         const float4 xo = *(const float4*)(xsrc_row(*p, l, b, t) + col);
;         float* dst = (isctx ? (float*)(p->ws + WS_XRC) + ((size_t)b * NCTX + t) * DM : p->out + ((size_t)b * NLAT + (t - NCTX)) * DM) + col;
;         *(float4*)dst = make_float4(xo.x + g.x * a.x, xo.y + g.y * a.y, xo.z + g.z * a.z, xo.w + g.w * a.w);
;       }
.LBB0_1098:
	v_ashrrev_i32_e32 v3, 5, v2
	v_add_u32_e32 v5, s20, v3
	v_mul_hi_i32 v6, v5, s55
	v_lshrrev_b32_e32 v7, 31, v6
	v_ashrrev_i32_e32 v6, 9, v6
	v_add_u32_e32 v8, v6, v7
	v_mul_i32_i24_e32 v6, 0x900, v8
	v_sub_u32_e32 v14, v5, v6
	v_mad_u32_u24 v12, v3, s66, v64
	s_mov_b64 s[6:7], 0x1a000
	v_lshl_add_u64 v[4:5], s[0:1], 0, v[0:1]
	v_lshl_add_u64 v[4:5], v[4:5], 0, s[6:7]
	global_load_dwordx4 v[48:51], v[4:5], off
	v_mov_b32_e32 v9, 0
	v_lshlrev_b64 v[8:9], 20, v[8:9]
	v_mov_b32_e32 v15, 0
	v_lshlrev_b64 v[14:15], 12, v[14:15]
	v_lshl_add_u64 v[8:9], v[8:9], 0, v[14:15]
	v_lshl_add_u64 v[8:9], v[8:9], 0, v[0:1]
	v_mov_b32_e32 v16, s68
	v_mov_b32_e32 v17, s69
	v_lshl_add_u64 v[16:17], v[16:17], 0, v[8:9]
	v_mov_b32_e32 v18, s13
	v_mov_b32_e32 v19, s14
	v_lshl_add_u64 v[18:19], v[18:19], 0, v[8:9]
	global_load_dwordx4 v[218:221], v[16:17], off
	s_mov_b64 s[6:7], 0x8000
	v_lshl_add_u64 v[4:5], v[16:17], 0, s[6:7]
	global_load_dwordx4 v[222:225], v[4:5], off
	s_mov_b64 s[6:7], 0x10000
	v_lshl_add_u64 v[4:5], v[16:17], 0, s[6:7]
	global_load_dwordx4 v[226:229], v[4:5], off
	s_mov_b64 s[6:7], 0x18000
	v_lshl_add_u64 v[4:5], v[16:17], 0, s[6:7]
	global_load_dwordx4 v[230:233], v[4:5], off
	s_mov_b64 s[6:7], 0x20000
	v_lshl_add_u64 v[4:5], v[16:17], 0, s[6:7]
	global_load_dwordx4 v[234:237], v[4:5], off
	s_mov_b64 s[6:7], 0x28000
	v_lshl_add_u64 v[4:5], v[16:17], 0, s[6:7]
	global_load_dwordx4 v[238:241], v[4:5], off
	s_mov_b64 s[6:7], 0x30000
	v_lshl_add_u64 v[4:5], v[16:17], 0, s[6:7]
	global_load_dwordx4 v[242:245], v[4:5], off
	s_mov_b64 s[6:7], 0x38000
	v_lshl_add_u64 v[4:5], v[16:17], 0, s[6:7]
	global_load_dwordx4 v[246:249], v[4:5], off
	ds_read_b128 v[32:35], v12
	ds_read_b128 v[36:39], v12 offset:4224
	ds_read_b128 v[40:43], v12 offset:8448
	ds_read_b128 v[44:47], v12 offset:12672
	s_waitcnt vmcnt(7) lgkmcnt(3)
	v_pk_fma_f32 v[32:33], v[32:33], v[48:49], v[218:219]
	v_pk_fma_f32 v[34:35], v[34:35], v[50:51], v[220:221]
	global_store_dwordx4 v[18:19], v[32:35], off
	s_mov_b64 s[6:7], 0x40000
	v_lshl_add_u64 v[6:7], v[16:17], 0, s[6:7]
	global_load_dwordx4 v[218:221], v[6:7], off
	ds_read_b128 v[32:35], v12 offset:16896
	s_waitcnt vmcnt(8) lgkmcnt(3)
	v_pk_fma_f32 v[36:37], v[36:37], v[48:49], v[222:223]
	v_pk_fma_f32 v[38:39], v[38:39], v[50:51], v[224:225]
	s_mov_b64 s[6:7], 0x8000
	v_lshl_add_u64 v[4:5], v[18:19], 0, s[6:7]
	global_store_dwordx4 v[4:5], v[36:39], off
	s_mov_b64 s[6:7], 0x48000
	v_lshl_add_u64 v[6:7], v[16:17], 0, s[6:7]
	global_load_dwordx4 v[222:225], v[6:7], off
	ds_read_b128 v[36:39], v12 offset:21120
	s_waitcnt vmcnt(9) lgkmcnt(3)
	v_pk_fma_f32 v[40:41], v[40:41], v[48:49], v[226:227]
	v_pk_fma_f32 v[42:43], v[42:43], v[50:51], v[228:229]
	s_mov_b64 s[6:7], 0x10000
	v_lshl_add_u64 v[4:5], v[18:19], 0, s[6:7]
	global_store_dwordx4 v[4:5], v[40:43], off
	s_mov_b64 s[6:7], 0x50000
	v_lshl_add_u64 v[6:7], v[16:17], 0, s[6:7]
	global_load_dwordx4 v[226:229], v[6:7], off
	ds_read_b128 v[40:43], v12 offset:25344
	s_waitcnt vmcnt(10) lgkmcnt(3)
	v_pk_fma_f32 v[44:45], v[44:45], v[48:49], v[230:231]
	v_pk_fma_f32 v[46:47], v[46:47], v[50:51], v[232:233]
	s_mov_b64 s[6:7], 0x18000
	v_lshl_add_u64 v[4:5], v[18:19], 0, s[6:7]
	global_store_dwordx4 v[4:5], v[44:47], off
	s_mov_b64 s[6:7], 0x58000
	v_lshl_add_u64 v[6:7], v[16:17], 0, s[6:7]
	global_load_dwordx4 v[230:233], v[6:7], off
	ds_read_b128 v[44:47], v12 offset:29568
	s_waitcnt vmcnt(11) lgkmcnt(3)
	v_pk_fma_f32 v[32:33], v[32:33], v[48:49], v[234:235]
	v_pk_fma_f32 v[34:35], v[34:35], v[50:51], v[236:237]
	s_mov_b64 s[6:7], 0x20000
	v_lshl_add_u64 v[4:5], v[18:19], 0, s[6:7]
	global_store_dwordx4 v[4:5], v[32:35], off
	s_mov_b64 s[6:7], 0x60000
	v_lshl_add_u64 v[6:7], v[16:17], 0, s[6:7]
	global_load_dwordx4 v[234:237], v[6:7], off
	ds_read_b128 v[32:35], v12 offset:33792
	s_waitcnt vmcnt(12) lgkmcnt(3)
;   DI void operator()(int mt, int nt, int wm, int wn, int r, int h, f32x16 (&acc)[WM][2]) const {
;     ...
; #pragma unroll 4
;       for (int j = 0; j < 16; ++j) {
;         const int id = tid + 256 * j;
;         const int lr = id >> 5, cc = id & 31;
;         const int row = mt * (WM * 64) + (lr >> 6) * (WM * 32) + ps * 64 + (lr & 63);
;         const int b = row / NTOK, t = row % NTOK;
;         const bool isctx = t < NCTX;
;         if (isctx && l == 1) continue;
;         const int col = nt * 128 + cc * 4;
;         const float4 a = *(const float4*)(T + lr * LD + cc * 4);
;         const float4 g = *(const float4*)(MOD + ((size_t)l * 9 + (isctx ? 8 : b)) * 3072 + 2048 + col);
;         const float4 xo = *(const float4*)(xsrc_row(*p, l, b, t) + col);
;         float* dst = (isctx ? (float*)(p->ws + WS_XRC) + ((size_t)b * NCTX + t) * DM : p->out + ((size_t)b * NLAT + (t - NCTX)) * DM) + col;
;         *(float4*)dst = make_float4(xo.x + g.x * a.x, xo.y + g.y * a.y, xo.z + g.z * a.z, xo.w + g.w * a.w);
;       }
	v_pk_fma_f32 v[36:37], v[36:37], v[48:49], v[238:239]
	v_pk_fma_f32 v[38:39], v[38:39], v[50:51], v[240:241]
	s_mov_b64 s[6:7], 0x28000
	v_lshl_add_u64 v[4:5], v[18:19], 0, s[6:7]
	global_store_dwordx4 v[4:5], v[36:39], off
	s_mov_b64 s[6:7], 0x68000
	v_lshl_add_u64 v[6:7], v[16:17], 0, s[6:7]
	global_load_dwordx4 v[238:241], v[6:7], off
	ds_read_b128 v[36:39], v12 offset:38016
	s_waitcnt vmcnt(13) lgkmcnt(3)
	v_pk_fma_f32 v[40:41], v[40:41], v[48:49], v[242:243]
	v_pk_fma_f32 v[42:43], v[42:43], v[50:51], v[244:245]
	s_mov_b64 s[6:7], 0x30000
	v_lshl_add_u64 v[4:5], v[18:19], 0, s[6:7]
	global_store_dwordx4 v[4:5], v[40:43], off
	s_mov_b64 s[6:7], 0x70000
	v_lshl_add_u64 v[6:7], v[16:17], 0, s[6:7]
	global_load_dwordx4 v[242:245], v[6:7], off
	ds_read_b128 v[40:43], v12 offset:42240
	s_waitcnt vmcnt(14) lgkmcnt(3)
	v_pk_fma_f32 v[44:45], v[44:45], v[48:49], v[246:247]
	v_pk_fma_f32 v[46:47], v[46:47], v[50:51], v[248:249]
	s_mov_b64 s[6:7], 0x38000
	v_lshl_add_u64 v[4:5], v[18:19], 0, s[6:7]
	global_store_dwordx4 v[4:5], v[44:47], off
	s_mov_b64 s[6:7], 0x78000
	v_lshl_add_u64 v[6:7], v[16:17], 0, s[6:7]
	global_load_dwordx4 v[246:249], v[6:7], off
	ds_read_b128 v[44:47], v12 offset:46464
	s_waitcnt vmcnt(14) lgkmcnt(3)
	v_pk_fma_f32 v[32:33], v[32:33], v[48:49], v[218:219]
	v_pk_fma_f32 v[34:35], v[34:35], v[50:51], v[220:221]
	s_mov_b64 s[6:7], 0x40000
	v_lshl_add_u64 v[4:5], v[18:19], 0, s[6:7]
	global_store_dwordx4 v[4:5], v[32:35], off
	s_nop 1
	ds_read_b128 v[32:35], v12 offset:50688
	s_waitcnt vmcnt(13) lgkmcnt(3)
	v_pk_fma_f32 v[36:37], v[36:37], v[48:49], v[222:223]
	v_pk_fma_f32 v[38:39], v[38:39], v[50:51], v[224:225]
	s_mov_b64 s[6:7], 0x48000
	v_lshl_add_u64 v[4:5], v[18:19], 0, s[6:7]
	global_store_dwordx4 v[4:5], v[36:39], off
	s_nop 1
	ds_read_b128 v[36:39], v12 offset:54912
	s_waitcnt vmcnt(12) lgkmcnt(3)
	v_pk_fma_f32 v[40:41], v[40:41], v[48:49], v[226:227]
	v_pk_fma_f32 v[42:43], v[42:43], v[50:51], v[228:229]
	s_mov_b64 s[6:7], 0x50000
	v_lshl_add_u64 v[4:5], v[18:19], 0, s[6:7]
	global_store_dwordx4 v[4:5], v[40:43], off
	s_nop 1
	ds_read_b128 v[40:43], v12 offset:59136
	s_waitcnt vmcnt(11) lgkmcnt(3)
	v_pk_fma_f32 v[44:45], v[44:45], v[48:49], v[230:231]
	v_pk_fma_f32 v[46:47], v[46:47], v[50:51], v[232:233]
	s_mov_b64 s[6:7], 0x58000
	v_lshl_add_u64 v[4:5], v[18:19], 0, s[6:7]
	global_store_dwordx4 v[4:5], v[44:47], off
	s_nop 1
	ds_read_b128 v[44:47], v12 offset:63360
	s_waitcnt vmcnt(10) lgkmcnt(3)
	v_pk_fma_f32 v[32:33], v[32:33], v[48:49], v[234:235]
	v_pk_fma_f32 v[34:35], v[34:35], v[50:51], v[236:237]
	s_mov_b64 s[6:7], 0x60000
	v_lshl_add_u64 v[4:5], v[18:19], 0, s[6:7]
	global_store_dwordx4 v[4:5], v[32:35], off
	s_waitcnt vmcnt(9) lgkmcnt(2)
	v_pk_fma_f32 v[36:37], v[36:37], v[48:49], v[238:239]
	v_pk_fma_f32 v[38:39], v[38:39], v[50:51], v[240:241]
	s_mov_b64 s[6:7], 0x68000
	v_lshl_add_u64 v[4:5], v[18:19], 0, s[6:7]
	global_store_dwordx4 v[4:5], v[36:39], off
	s_waitcnt vmcnt(8) lgkmcnt(1)
	v_pk_fma_f32 v[40:41], v[40:41], v[48:49], v[242:243]
	v_pk_fma_f32 v[42:43], v[42:43], v[50:51], v[244:245]
	s_mov_b64 s[6:7], 0x70000
	v_lshl_add_u64 v[4:5], v[18:19], 0, s[6:7]
	global_store_dwordx4 v[4:5], v[40:43], off
	s_waitcnt vmcnt(7) lgkmcnt(0)
	v_pk_fma_f32 v[44:45], v[44:45], v[48:49], v[246:247]
	v_pk_fma_f32 v[46:47], v[46:47], v[50:51], v[248:249]
	s_mov_b64 s[6:7], 0x78000
	v_lshl_add_u64 v[4:5], v[18:19], 0, s[6:7]
	global_store_dwordx4 v[4:5], v[44:47], off
	v_readlane_b32 s4, v253, 58
	s_add_i32 s19, s19, s4
	v_readlane_b32 s68, v254, 21
	s_cmp_lt_i32 s19, s26
	v_readlane_b32 s69, v254, 22
	s_cbranch_scc1 .LBB0_1085
